# EpiQK epilogue: replace 15 redundant vmcnt(0) store-drain waits per rope unit with s_nop 1
# speedup vs baseline: 1.0042x; 1.0042x over previous
; __device__ __forceinline__ unsigned cvt_pk_bf16(float lo, float hi) { unsigned r; asm("v_cvt_pk_bf16_f32 %0, %1, %2" : "=v"(r) : "v"(lo), "v"(hi)); return r; }
;     __device__ __forceinline__ void operator()(const AccT& acc, const Unit& u, int wr, int wc, int fr, int fq) const {
;     ...
; #pragma unroll
;         for (int ai = 0; ai < 2; ++ai)
; #pragma unroll
;             for (int m = 0; m < 4; ++m) {
;                 const int rl = ai * 128 + wr * 64 + m * 16 + fr;
;                 bf16_t* rowp = base + (size_t)(u.pm * 256 + rl) * ldo + hh * 256 + wc * 32 + 8 * fq;
; #pragma unroll
;                 for (int bj = 0; bj < 2; ++bj) {
;                     f32x4 v0 = acc[ai][bj][m][0], v1 = acc[ai][bj][m][1];
;                     if (lat) {
;                         const f32x4 c01 = bj ? ctC[m][0] : ctR[ai][0], c23 = bj ? ctC[m][1] : ctR[ai][1];
;                         f32x4 r0, r1;
;                         r0[0] = v0[0] * c01[0] - v0[1] * c01[1]; r0[1] = v0[0] * c01[1] + v0[1] * c01[0];
;                         r0[2] = v0[2] * c01[2] - v0[3] * c01[3]; r0[3] = v0[2] * c01[3] + v0[3] * c01[2];
;                         r1[0] = v1[0] * c23[0] - v1[1] * c23[1]; r1[1] = v1[0] * c23[1] + v1[1] * c23[0];
;                         r1[2] = v1[2] * c23[2] - v1[3] * c23[3]; r1[3] = v1[2] * c23[3] + v1[3] * c23[2];
;                         v0 = r0; v1 = r1;
;                     }
;                     v0 = v0 * osc; v1 = v1 * osc;
;                     u32x4 w; w.x = cvt_pk_bf16(v0[0], v0[1]); w.y = cvt_pk_bf16(v0[2], v0[3]); w.z = cvt_pk_bf16(v1[0], v1[1]); w.w = cvt_pk_bf16(v1[2], v1[3]);
;                     *(u32x4*)(rowp + bj * 128) = w;
.LBB0_336:
	s_add_i32 s76, s11, -8
	s_lshl_b64 s[52:53], s[76:77], 9
	s_add_u32 s15, s48, s52
	s_addc_u32 s64, s49, s53
	s_and_b64 s[52:53], s[60:61], exec
	s_cselect_b32 s15, s40, s15
	s_cselect_b32 s64, s41, s64
	s_cmp_lt_i32 s11, 4
	s_cselect_b64 vcc, -1, 0
	s_and_b64 s[52:53], vcc, exec
	s_cselect_b32 s64, s35, s64
	s_cselect_b32 s15, s34, s15
	s_lshl_b32 s11, s11, 8
	s_and_b32 s11, s11, 0x300
	s_and_b64 s[52:53], s[60:61], exec
	s_cselect_b32 s52, s11, 0
	s_lshl_b32 s10, s10, 8
	s_add_i32 s10, s10, s44
	v_add_u32_e32 v194, s10, v194
	s_and_b64 s[10:11], s[60:61], exec
	s_cselect_b32 s10, 10, 11
	s_lshl_b32 s11, s52, 1
	s_add_u32 s11, s15, s11
	s_addc_u32 s15, s64, 0
	s_add_u32 s52, s11, s70
	v_lshlrev_b32_e32 v196, 3, v193
	v_mov_b32_e32 v192, 0x3d800000
	s_addc_u32 s53, s15, 0
	v_ashrrev_i32_e32 v197, 31, v196
	v_ashrrev_i32_e32 v195, 31, v194
	v_cndmask_b32_e32 v192, 1.0, v192, vcc
	v_lshl_add_u64 v[196:197], v[196:197], 1, s[52:53]
	v_lshlrev_b64 v[198:199], s10, v[194:195]
	v_lshl_add_u64 v[198:199], v[198:199], 1, v[196:197]
	v_pk_mul_f32 v[204:205], v[192:193], v[164:165] op_sel_hi:[0,1]
	v_pk_mul_f32 v[164:165], v[192:193], v[162:163] op_sel_hi:[0,1]
	s_and_b64 vcc, exec, s[4:5]
	v_pk_mul_f32 v[168:169], v[192:193], v[168:169] op_sel_hi:[0,1]
	v_pk_mul_f32 v[166:167], v[192:193], v[166:167] op_sel_hi:[0,1]
	v_cvt_pk_bf16_f32 v162, v166, v167
	v_cvt_pk_bf16_f32 v163, v168, v169
	v_cvt_pk_bf16_f32 v164, v164, v165
	v_cvt_pk_bf16_f32 v165, v204, v205
	global_store_dwordx4 v[198:199], v[162:165], off
	s_cbranch_vccnz .LBB0_338
	s_nop 1
	v_pk_mul_f32 v[164:165], v[150:151], v[158:159] op_sel:[1,1] op_sel_hi:[1,0]
	v_pk_mul_f32 v[162:163], v[150:151], v[158:159]
	v_pk_fma_f32 v[150:151], v[150:151], v[158:159], v[164:165] op_sel_hi:[0,1,1]
	v_mul_f32_e32 v150, v153, v161
	v_pk_fma_f32 v[166:167], v[152:153], v[160:161], v[150:151] op_sel_hi:[1,1,0] neg_lo:[0,0,1] neg_hi:[0,0,1]
	v_mul_f32_e32 v150, v153, v160
	v_pk_mul_f32 v[204:205], v[146:147], v[154:155] op_sel:[1,1] op_sel_hi:[1,0]
	v_pk_fma_f32 v[168:169], v[152:153], v[160:161], v[150:151] op_sel:[0,1,0] op_sel_hi:[1,0,0]
	v_pk_mul_f32 v[152:153], v[146:147], v[154:155]
	v_pk_fma_f32 v[146:147], v[146:147], v[154:155], v[204:205] op_sel_hi:[0,1,1]
	v_mul_f32_e32 v146, v149, v157
	v_pk_fma_f32 v[206:207], v[148:149], v[156:157], v[146:147] op_sel_hi:[1,1,0] neg_lo:[0,0,1] neg_hi:[0,0,1]
	v_mul_f32_e32 v146, v149, v156
	v_pk_fma_f32 v[208:209], v[148:149], v[156:157], v[146:147] op_sel:[0,1,0] op_sel_hi:[1,0,0]
	v_sub_f32_e32 v150, v162, v164
	v_sub_f32_e32 v146, v152, v204
	v_mov_b32_e32 v152, v166
	v_mov_b32_e32 v153, v168
	v_mov_b32_e32 v148, v206
	v_mov_b32_e32 v149, v208
.LBB0_338:
	v_mov_b32_e32 v193, v192
	v_mov_b32_e32 v162, v192
	v_mov_b32_e32 v163, v192
	v_pk_mul_f32 v[164:165], v[162:163], v[148:149]
	v_pk_mul_f32 v[148:149], v[192:193], v[146:147]
	s_and_b64 vcc, exec, s[4:5]
	v_pk_mul_f32 v[152:153], v[162:163], v[152:153]
	v_pk_mul_f32 v[150:151], v[192:193], v[150:151]
	v_cvt_pk_bf16_f32 v147, v152, v153
	v_cvt_pk_bf16_f32 v148, v148, v149
	v_cvt_pk_bf16_f32 v149, v164, v165
	s_nop 0
	v_cvt_pk_bf16_f32 v146, v150, v151
	global_store_dwordx4 v[198:199], v[146:149], off offset:256
	s_cbranch_vccnz .LBB0_340
	s_nop 1
	v_pk_mul_f32 v[148:149], v[142:143], v[174:175] op_sel:[1,1] op_sel_hi:[1,0]
	v_pk_mul_f32 v[146:147], v[142:143], v[174:175]
	v_pk_fma_f32 v[142:143], v[142:143], v[174:175], v[148:149] op_sel_hi:[0,1,1]
	v_mul_f32_e32 v142, v145, v177
	v_pk_fma_f32 v[150:151], v[144:145], v[176:177], v[142:143] op_sel_hi:[1,1,0] neg_lo:[0,0,1] neg_hi:[0,0,1]
	v_mul_f32_e32 v142, v145, v176
	v_pk_mul_f32 v[164:165], v[138:139], v[170:171] op_sel:[1,1] op_sel_hi:[1,0]
	v_pk_fma_f32 v[152:153], v[144:145], v[176:177], v[142:143] op_sel:[0,1,0] op_sel_hi:[1,0,0]
	v_pk_mul_f32 v[144:145], v[138:139], v[170:171]
	v_pk_fma_f32 v[138:139], v[138:139], v[170:171], v[164:165] op_sel_hi:[0,1,1]
	v_mul_f32_e32 v138, v141, v173
	v_pk_fma_f32 v[166:167], v[140:141], v[172:173], v[138:139] op_sel_hi:[1,1,0] neg_lo:[0,0,1] neg_hi:[0,0,1]
	v_mul_f32_e32 v138, v141, v172
	v_pk_fma_f32 v[168:169], v[140:141], v[172:173], v[138:139] op_sel:[0,1,0] op_sel_hi:[1,0,0]
	v_sub_f32_e32 v142, v146, v148
	v_sub_f32_e32 v138, v144, v164
	v_mov_b32_e32 v144, v150
	v_mov_b32_e32 v145, v152
	v_mov_b32_e32 v140, v166
	v_mov_b32_e32 v141, v168
.LBB0_340:
	s_nop 0
	v_add_u32_e32 v146, 16, v194
	v_ashrrev_i32_e32 v147, 31, v146
	v_lshlrev_b64 v[146:147], s10, v[146:147]
	v_lshl_add_u64 v[146:147], v[146:147], 1, v[196:197]
	v_pk_mul_f32 v[148:149], v[162:163], v[140:141]
	v_pk_mul_f32 v[140:141], v[192:193], v[138:139]
	s_and_b64 vcc, exec, s[4:5]
	v_pk_mul_f32 v[144:145], v[162:163], v[144:145]
	v_pk_mul_f32 v[142:143], v[192:193], v[142:143]
	v_cvt_pk_bf16_f32 v139, v144, v145
	v_cvt_pk_bf16_f32 v140, v140, v141
	v_cvt_pk_bf16_f32 v141, v148, v149
	s_nop 0
	v_cvt_pk_bf16_f32 v138, v142, v143
	global_store_dwordx4 v[146:147], v[138:141], off
	s_cbranch_vccnz .LBB0_342
	s_nop 1
	v_pk_mul_f32 v[140:141], v[126:127], v[134:135] op_sel:[1,1] op_sel_hi:[1,0]
	v_pk_mul_f32 v[138:139], v[126:127], v[134:135]
	v_pk_fma_f32 v[126:127], v[126:127], v[134:135], v[140:141] op_sel_hi:[0,1,1]
	v_mul_f32_e32 v126, v129, v137
	v_pk_fma_f32 v[142:143], v[128:129], v[136:137], v[126:127] op_sel_hi:[1,1,0] neg_lo:[0,0,1] neg_hi:[0,0,1]
	v_mul_f32_e32 v126, v129, v136
	v_pk_mul_f32 v[148:149], v[122:123], v[130:131] op_sel:[1,1] op_sel_hi:[1,0]
	v_pk_fma_f32 v[144:145], v[128:129], v[136:137], v[126:127] op_sel:[0,1,0] op_sel_hi:[1,0,0]
	v_pk_mul_f32 v[128:129], v[122:123], v[130:131]
	v_pk_fma_f32 v[122:123], v[122:123], v[130:131], v[148:149] op_sel_hi:[0,1,1]
	v_mul_f32_e32 v122, v125, v133
	v_pk_fma_f32 v[150:151], v[124:125], v[132:133], v[122:123] op_sel_hi:[1,1,0] neg_lo:[0,0,1] neg_hi:[0,0,1]
	v_mul_f32_e32 v122, v125, v132
	v_pk_fma_f32 v[152:153], v[124:125], v[132:133], v[122:123] op_sel:[0,1,0] op_sel_hi:[1,0,0]
	v_sub_f32_e32 v126, v138, v140
	v_sub_f32_e32 v122, v128, v148
	v_mov_b32_e32 v128, v142
	v_mov_b32_e32 v129, v144
	v_mov_b32_e32 v124, v150
	v_mov_b32_e32 v125, v152
; __device__ __forceinline__ unsigned cvt_pk_bf16(float lo, float hi) { unsigned r; asm("v_cvt_pk_bf16_f32 %0, %1, %2" : "=v"(r) : "v"(lo), "v"(hi)); return r; }
;     __device__ __forceinline__ void operator()(const AccT& acc, const Unit& u, int wr, int wc, int fr, int fq) const {
;     ...
; #pragma unroll
;         for (int ai = 0; ai < 2; ++ai)
; #pragma unroll
;             for (int m = 0; m < 4; ++m) {
;                 const int rl = ai * 128 + wr * 64 + m * 16 + fr;
;                 bf16_t* rowp = base + (size_t)(u.pm * 256 + rl) * ldo + hh * 256 + wc * 32 + 8 * fq;
; #pragma unroll
;                 for (int bj = 0; bj < 2; ++bj) {
;                     f32x4 v0 = acc[ai][bj][m][0], v1 = acc[ai][bj][m][1];
;                     if (lat) {
;                         const f32x4 c01 = bj ? ctC[m][0] : ctR[ai][0], c23 = bj ? ctC[m][1] : ctR[ai][1];
;                         f32x4 r0, r1;
;                         r0[0] = v0[0] * c01[0] - v0[1] * c01[1]; r0[1] = v0[0] * c01[1] + v0[1] * c01[0];
;                         r0[2] = v0[2] * c01[2] - v0[3] * c01[3]; r0[3] = v0[2] * c01[3] + v0[3] * c01[2];
;                         r1[0] = v1[0] * c23[0] - v1[1] * c23[1]; r1[1] = v1[0] * c23[1] + v1[1] * c23[0];
;                         r1[2] = v1[2] * c23[2] - v1[3] * c23[3]; r1[3] = v1[2] * c23[3] + v1[3] * c23[2];
;                         v0 = r0; v1 = r1;
;                     }
;                     v0 = v0 * osc; v1 = v1 * osc;
;                     u32x4 w; w.x = cvt_pk_bf16(v0[0], v0[1]); w.y = cvt_pk_bf16(v0[2], v0[3]); w.z = cvt_pk_bf16(v1[0], v1[1]); w.w = cvt_pk_bf16(v1[2], v1[3]);
;                     *(u32x4*)(rowp + bj * 128) = w;
.LBB0_342:
	s_nop 0
	v_mov_b32_e32 v138, v192
	v_mov_b32_e32 v139, v192
	v_pk_mul_f32 v[140:141], v[138:139], v[124:125]
	v_pk_mul_f32 v[124:125], v[192:193], v[122:123]
	s_and_b64 vcc, exec, s[4:5]
	v_pk_mul_f32 v[128:129], v[138:139], v[128:129]
	v_pk_mul_f32 v[126:127], v[192:193], v[126:127]
	v_cvt_pk_bf16_f32 v123, v128, v129
	v_cvt_pk_bf16_f32 v124, v124, v125
	v_cvt_pk_bf16_f32 v125, v140, v141
	s_nop 0
	v_cvt_pk_bf16_f32 v122, v126, v127
	global_store_dwordx4 v[146:147], v[122:125], off offset:256
	s_cbranch_vccnz .LBB0_344
	s_nop 1
	v_pk_mul_f32 v[124:125], v[118:119], v[174:175] op_sel:[1,1] op_sel_hi:[1,0]
	v_pk_mul_f32 v[122:123], v[118:119], v[174:175]
	v_pk_fma_f32 v[118:119], v[118:119], v[174:175], v[124:125] op_sel_hi:[0,1,1]
	v_mul_f32_e32 v118, v121, v177
	v_pk_fma_f32 v[126:127], v[120:121], v[176:177], v[118:119] op_sel_hi:[1,1,0] neg_lo:[0,0,1] neg_hi:[0,0,1]
	v_mul_f32_e32 v118, v121, v176
	v_pk_mul_f32 v[140:141], v[114:115], v[170:171] op_sel:[1,1] op_sel_hi:[1,0]
	v_pk_fma_f32 v[128:129], v[120:121], v[176:177], v[118:119] op_sel:[0,1,0] op_sel_hi:[1,0,0]
	v_pk_mul_f32 v[120:121], v[114:115], v[170:171]
	v_pk_fma_f32 v[114:115], v[114:115], v[170:171], v[140:141] op_sel_hi:[0,1,1]
	v_mul_f32_e32 v114, v117, v173
	v_pk_fma_f32 v[142:143], v[116:117], v[172:173], v[114:115] op_sel_hi:[1,1,0] neg_lo:[0,0,1] neg_hi:[0,0,1]
	v_mul_f32_e32 v114, v117, v172
	v_pk_fma_f32 v[144:145], v[116:117], v[172:173], v[114:115] op_sel:[0,1,0] op_sel_hi:[1,0,0]
	v_sub_f32_e32 v118, v122, v124
	v_sub_f32_e32 v114, v120, v140
	v_mov_b32_e32 v120, v126
	v_mov_b32_e32 v121, v128
	v_mov_b32_e32 v116, v142
	v_mov_b32_e32 v117, v144
.LBB0_344:
	s_nop 0
	v_add_u32_e32 v122, 32, v194
	v_ashrrev_i32_e32 v123, 31, v122
	v_lshlrev_b64 v[122:123], s10, v[122:123]
	v_lshl_add_u64 v[122:123], v[122:123], 1, v[196:197]
	v_pk_mul_f32 v[124:125], v[138:139], v[116:117]
	v_pk_mul_f32 v[116:117], v[192:193], v[114:115]
	s_and_b64 vcc, exec, s[4:5]
	v_pk_mul_f32 v[120:121], v[138:139], v[120:121]
	v_pk_mul_f32 v[118:119], v[192:193], v[118:119]
	v_cvt_pk_bf16_f32 v115, v120, v121
	v_cvt_pk_bf16_f32 v116, v116, v117
	v_cvt_pk_bf16_f32 v117, v124, v125
	s_nop 0
	v_cvt_pk_bf16_f32 v114, v118, v119
	global_store_dwordx4 v[122:123], v[114:117], off
	s_cbranch_vccnz .LBB0_346
	s_nop 1
	v_pk_mul_f32 v[116:117], v[102:103], v[110:111] op_sel:[1,1] op_sel_hi:[1,0]
	v_pk_mul_f32 v[114:115], v[102:103], v[110:111]
	v_pk_fma_f32 v[102:103], v[102:103], v[110:111], v[116:117] op_sel_hi:[0,1,1]
	v_mul_f32_e32 v102, v105, v113
	v_pk_fma_f32 v[118:119], v[104:105], v[112:113], v[102:103] op_sel_hi:[1,1,0] neg_lo:[0,0,1] neg_hi:[0,0,1]
	v_mul_f32_e32 v102, v105, v112
	v_pk_mul_f32 v[124:125], v[98:99], v[106:107] op_sel:[1,1] op_sel_hi:[1,0]
	v_pk_fma_f32 v[120:121], v[104:105], v[112:113], v[102:103] op_sel:[0,1,0] op_sel_hi:[1,0,0]
	v_pk_mul_f32 v[104:105], v[98:99], v[106:107]
	v_pk_fma_f32 v[98:99], v[98:99], v[106:107], v[124:125] op_sel_hi:[0,1,1]
	v_mul_f32_e32 v98, v101, v109
	v_pk_fma_f32 v[126:127], v[100:101], v[108:109], v[98:99] op_sel_hi:[1,1,0] neg_lo:[0,0,1] neg_hi:[0,0,1]
	v_mul_f32_e32 v98, v101, v108
	v_pk_fma_f32 v[128:129], v[100:101], v[108:109], v[98:99] op_sel:[0,1,0] op_sel_hi:[1,0,0]
	v_sub_f32_e32 v102, v114, v116
	v_sub_f32_e32 v98, v104, v124
	v_mov_b32_e32 v104, v118
	v_mov_b32_e32 v105, v120
	v_mov_b32_e32 v100, v126
	v_mov_b32_e32 v101, v128
.LBB0_346:
	s_nop 0
	v_mov_b32_e32 v114, v192
	v_mov_b32_e32 v115, v192
	v_pk_mul_f32 v[116:117], v[114:115], v[100:101]
	v_pk_mul_f32 v[100:101], v[192:193], v[98:99]
	s_and_b64 vcc, exec, s[4:5]
	v_pk_mul_f32 v[104:105], v[114:115], v[104:105]
	v_pk_mul_f32 v[102:103], v[192:193], v[102:103]
	v_cvt_pk_bf16_f32 v99, v104, v105
	v_cvt_pk_bf16_f32 v100, v100, v101
	v_cvt_pk_bf16_f32 v101, v116, v117
	s_nop 0
	v_cvt_pk_bf16_f32 v98, v102, v103
	global_store_dwordx4 v[122:123], v[98:101], off offset:256
	s_cbranch_vccnz .LBB0_348
	s_nop 1
	v_pk_mul_f32 v[100:101], v[90:91], v[174:175] op_sel:[1,1] op_sel_hi:[1,0]
	v_pk_mul_f32 v[98:99], v[90:91], v[174:175]
	v_pk_fma_f32 v[90:91], v[90:91], v[174:175], v[100:101] op_sel_hi:[0,1,1]
	v_mul_f32_e32 v90, v93, v177
	v_pk_fma_f32 v[102:103], v[92:93], v[176:177], v[90:91] op_sel_hi:[1,1,0] neg_lo:[0,0,1] neg_hi:[0,0,1]
	v_mul_f32_e32 v90, v93, v176
	v_pk_mul_f32 v[116:117], v[78:79], v[170:171] op_sel:[1,1] op_sel_hi:[1,0]
	v_pk_fma_f32 v[104:105], v[92:93], v[176:177], v[90:91] op_sel:[0,1,0] op_sel_hi:[1,0,0]
	v_pk_mul_f32 v[92:93], v[78:79], v[170:171]
	v_pk_fma_f32 v[78:79], v[78:79], v[170:171], v[116:117] op_sel_hi:[0,1,1]
	v_mul_f32_e32 v78, v81, v173
	v_pk_fma_f32 v[118:119], v[80:81], v[172:173], v[78:79] op_sel_hi:[1,1,0] neg_lo:[0,0,1] neg_hi:[0,0,1]
	v_mul_f32_e32 v78, v81, v172
	v_pk_fma_f32 v[120:121], v[80:81], v[172:173], v[78:79] op_sel:[0,1,0] op_sel_hi:[1,0,0]
	v_sub_f32_e32 v90, v98, v100
	v_sub_f32_e32 v78, v92, v116
	v_mov_b32_e32 v92, v102
	v_mov_b32_e32 v93, v104
	v_mov_b32_e32 v80, v118
	v_mov_b32_e32 v81, v120
; __device__ __forceinline__ unsigned cvt_pk_bf16(float lo, float hi) { unsigned r; asm("v_cvt_pk_bf16_f32 %0, %1, %2" : "=v"(r) : "v"(lo), "v"(hi)); return r; }
;     __device__ __forceinline__ void operator()(const AccT& acc, const Unit& u, int wr, int wc, int fr, int fq) const {
;     ...
; #pragma unroll
;         for (int ai = 0; ai < 2; ++ai)
; #pragma unroll
;             for (int m = 0; m < 4; ++m) {
;                 const int rl = ai * 128 + wr * 64 + m * 16 + fr;
;                 bf16_t* rowp = base + (size_t)(u.pm * 256 + rl) * ldo + hh * 256 + wc * 32 + 8 * fq;
; #pragma unroll
;                 for (int bj = 0; bj < 2; ++bj) {
;                     f32x4 v0 = acc[ai][bj][m][0], v1 = acc[ai][bj][m][1];
;                     if (lat) {
;                         const f32x4 c01 = bj ? ctC[m][0] : ctR[ai][0], c23 = bj ? ctC[m][1] : ctR[ai][1];
;                         f32x4 r0, r1;
;                         r0[0] = v0[0] * c01[0] - v0[1] * c01[1]; r0[1] = v0[0] * c01[1] + v0[1] * c01[0];
;                         r0[2] = v0[2] * c01[2] - v0[3] * c01[3]; r0[3] = v0[2] * c01[3] + v0[3] * c01[2];
;                         r1[0] = v1[0] * c23[0] - v1[1] * c23[1]; r1[1] = v1[0] * c23[1] + v1[1] * c23[0];
;                         r1[2] = v1[2] * c23[2] - v1[3] * c23[3]; r1[3] = v1[2] * c23[3] + v1[3] * c23[2];
;                         v0 = r0; v1 = r1;
;                     }
;                     v0 = v0 * osc; v1 = v1 * osc;
;                     u32x4 w; w.x = cvt_pk_bf16(v0[0], v0[1]); w.y = cvt_pk_bf16(v0[2], v0[3]); w.z = cvt_pk_bf16(v1[0], v1[1]); w.w = cvt_pk_bf16(v1[2], v1[3]);
;                     *(u32x4*)(rowp + bj * 128) = w;
.LBB0_348:
	s_nop 0
	v_add_u32_e32 v98, 48, v194
	v_ashrrev_i32_e32 v99, 31, v98
	v_lshlrev_b64 v[98:99], s10, v[98:99]
	v_lshl_add_u64 v[98:99], v[98:99], 1, v[196:197]
	v_pk_mul_f32 v[100:101], v[114:115], v[80:81]
	v_pk_mul_f32 v[80:81], v[192:193], v[78:79]
	s_and_b64 vcc, exec, s[4:5]
	v_pk_mul_f32 v[92:93], v[114:115], v[92:93]
	v_pk_mul_f32 v[90:91], v[192:193], v[90:91]
	v_cvt_pk_bf16_f32 v79, v92, v93
	v_cvt_pk_bf16_f32 v80, v80, v81
	v_cvt_pk_bf16_f32 v81, v100, v101
	s_nop 0
	v_cvt_pk_bf16_f32 v78, v90, v91
	global_store_dwordx4 v[98:99], v[78:81], off
	s_cbranch_vccnz .LBB0_350
	s_nop 1
	v_pk_mul_f32 v[80:81], v[70:71], v[82:83] op_sel:[1,1] op_sel_hi:[1,0]
	v_pk_mul_f32 v[78:79], v[70:71], v[82:83]
	v_pk_fma_f32 v[70:71], v[70:71], v[82:83], v[80:81] op_sel_hi:[0,1,1]
	v_mul_f32_e32 v70, v73, v85
	v_pk_fma_f32 v[90:91], v[72:73], v[84:85], v[70:71] op_sel_hi:[1,1,0] neg_lo:[0,0,1] neg_hi:[0,0,1]
	v_mul_f32_e32 v70, v73, v84
	v_pk_mul_f32 v[100:101], v[66:67], v[74:75] op_sel:[1,1] op_sel_hi:[1,0]
	v_pk_fma_f32 v[92:93], v[72:73], v[84:85], v[70:71] op_sel:[0,1,0] op_sel_hi:[1,0,0]
	v_pk_mul_f32 v[72:73], v[66:67], v[74:75]
	v_pk_fma_f32 v[66:67], v[66:67], v[74:75], v[100:101] op_sel_hi:[0,1,1]
	v_mul_f32_e32 v66, v69, v77
	v_pk_fma_f32 v[102:103], v[68:69], v[76:77], v[66:67] op_sel_hi:[1,1,0] neg_lo:[0,0,1] neg_hi:[0,0,1]
	v_mul_f32_e32 v66, v69, v76
	v_pk_fma_f32 v[104:105], v[68:69], v[76:77], v[66:67] op_sel:[0,1,0] op_sel_hi:[1,0,0]
	v_sub_f32_e32 v70, v78, v80
	v_sub_f32_e32 v66, v72, v100
	v_mov_b32_e32 v72, v90
	v_mov_b32_e32 v73, v92
	v_mov_b32_e32 v68, v102
	v_mov_b32_e32 v69, v104
.LBB0_350:
	s_nop 0
	v_mov_b32_e32 v78, v192
	v_mov_b32_e32 v79, v192
	v_pk_mul_f32 v[80:81], v[78:79], v[68:69]
	v_pk_mul_f32 v[68:69], v[192:193], v[66:67]
	s_and_b64 vcc, exec, s[4:5]
	v_pk_mul_f32 v[72:73], v[78:79], v[72:73]
	v_pk_mul_f32 v[70:71], v[192:193], v[70:71]
	v_cvt_pk_bf16_f32 v67, v72, v73
	v_cvt_pk_bf16_f32 v68, v68, v69
	v_cvt_pk_bf16_f32 v69, v80, v81
	s_nop 0
	v_cvt_pk_bf16_f32 v66, v70, v71
	global_store_dwordx4 v[98:99], v[66:69], off offset:256
	s_cbranch_vccnz .LBB0_352
	s_nop 1
	v_pk_mul_f32 v[68:69], v[62:63], v[94:95] op_sel:[1,1] op_sel_hi:[1,0]
	v_pk_mul_f32 v[66:67], v[62:63], v[94:95]
	v_pk_fma_f32 v[62:63], v[62:63], v[94:95], v[68:69] op_sel_hi:[0,1,1]
	v_mul_f32_e32 v62, v65, v97
	v_pk_fma_f32 v[70:71], v[64:65], v[96:97], v[62:63] op_sel_hi:[1,1,0] neg_lo:[0,0,1] neg_hi:[0,0,1]
	v_mul_f32_e32 v62, v65, v96
	v_pk_mul_f32 v[80:81], v[58:59], v[86:87] op_sel:[1,1] op_sel_hi:[1,0]
	v_pk_fma_f32 v[72:73], v[64:65], v[96:97], v[62:63] op_sel:[0,1,0] op_sel_hi:[1,0,0]
	v_pk_mul_f32 v[64:65], v[58:59], v[86:87]
	v_pk_fma_f32 v[58:59], v[58:59], v[86:87], v[80:81] op_sel_hi:[0,1,1]
	v_mul_f32_e32 v58, v61, v89
	v_pk_fma_f32 v[90:91], v[60:61], v[88:89], v[58:59] op_sel_hi:[1,1,0] neg_lo:[0,0,1] neg_hi:[0,0,1]
	v_mul_f32_e32 v58, v61, v88
	v_pk_fma_f32 v[92:93], v[60:61], v[88:89], v[58:59] op_sel:[0,1,0] op_sel_hi:[1,0,0]
	v_sub_f32_e32 v62, v66, v68
	v_sub_f32_e32 v58, v64, v80
	v_mov_b32_e32 v64, v70
	v_mov_b32_e32 v65, v72
	v_mov_b32_e32 v60, v90
	v_mov_b32_e32 v61, v92
.LBB0_352:
	s_nop 0
	v_add_u32_e32 v66, 0x80, v194
	v_ashrrev_i32_e32 v67, 31, v66
	v_lshlrev_b64 v[66:67], s10, v[66:67]
	v_lshl_add_u64 v[66:67], v[66:67], 1, v[196:197]
	v_pk_mul_f32 v[68:69], v[78:79], v[60:61]
	v_pk_mul_f32 v[60:61], v[192:193], v[58:59]
	s_and_b64 vcc, exec, s[4:5]
	v_pk_mul_f32 v[64:65], v[78:79], v[64:65]
	v_pk_mul_f32 v[62:63], v[192:193], v[62:63]
	v_cvt_pk_bf16_f32 v59, v64, v65
	v_cvt_pk_bf16_f32 v60, v60, v61
	v_cvt_pk_bf16_f32 v61, v68, v69
	s_nop 0
	v_cvt_pk_bf16_f32 v58, v62, v63
	global_store_dwordx4 v[66:67], v[58:61], off
	s_cbranch_vccnz .LBB0_354
	s_nop 1
	v_pk_mul_f32 v[60:61], v[54:55], v[158:159] op_sel:[1,1] op_sel_hi:[1,0]
	v_pk_mul_f32 v[58:59], v[54:55], v[158:159]
	v_pk_fma_f32 v[54:55], v[54:55], v[158:159], v[60:61] op_sel_hi:[0,1,1]
	v_mul_f32_e32 v54, v57, v161
	v_pk_fma_f32 v[62:63], v[56:57], v[160:161], v[54:55] op_sel_hi:[1,1,0] neg_lo:[0,0,1] neg_hi:[0,0,1]
	v_mul_f32_e32 v54, v57, v160
	v_pk_mul_f32 v[68:69], v[50:51], v[154:155] op_sel:[1,1] op_sel_hi:[1,0]
	v_pk_fma_f32 v[64:65], v[56:57], v[160:161], v[54:55] op_sel:[0,1,0] op_sel_hi:[1,0,0]
	v_pk_mul_f32 v[56:57], v[50:51], v[154:155]
	v_pk_fma_f32 v[50:51], v[50:51], v[154:155], v[68:69] op_sel_hi:[0,1,1]
	v_mul_f32_e32 v50, v53, v157
	v_pk_fma_f32 v[70:71], v[52:53], v[156:157], v[50:51] op_sel_hi:[1,1,0] neg_lo:[0,0,1] neg_hi:[0,0,1]
	v_mul_f32_e32 v50, v53, v156
	v_pk_fma_f32 v[72:73], v[52:53], v[156:157], v[50:51] op_sel:[0,1,0] op_sel_hi:[1,0,0]
	v_sub_f32_e32 v54, v58, v60
	v_sub_f32_e32 v50, v56, v68
	v_mov_b32_e32 v56, v62
	v_mov_b32_e32 v57, v64
	v_mov_b32_e32 v52, v70
	v_mov_b32_e32 v53, v72
.LBB0_354:
	s_nop 0
	v_mov_b32_e32 v58, v192
	v_mov_b32_e32 v59, v192
	v_pk_mul_f32 v[60:61], v[58:59], v[52:53]
	v_pk_mul_f32 v[52:53], v[192:193], v[50:51]
	s_and_b64 vcc, exec, s[4:5]
	v_pk_mul_f32 v[56:57], v[58:59], v[56:57]
	v_pk_mul_f32 v[54:55], v[192:193], v[54:55]
	v_cvt_pk_bf16_f32 v51, v56, v57
	v_cvt_pk_bf16_f32 v52, v52, v53
	v_cvt_pk_bf16_f32 v53, v60, v61
	s_nop 0
	v_cvt_pk_bf16_f32 v50, v54, v55
	global_store_dwordx4 v[66:67], v[50:53], off offset:256
	s_cbranch_vccnz .LBB0_356
	s_nop 1
	v_pk_mul_f32 v[52:53], v[46:47], v[94:95] op_sel:[1,1] op_sel_hi:[1,0]
	v_pk_mul_f32 v[50:51], v[46:47], v[94:95]
	v_pk_fma_f32 v[46:47], v[46:47], v[94:95], v[52:53] op_sel_hi:[0,1,1]
	v_mul_f32_e32 v46, v49, v97
	v_pk_fma_f32 v[54:55], v[48:49], v[96:97], v[46:47] op_sel_hi:[1,1,0] neg_lo:[0,0,1] neg_hi:[0,0,1]
	v_mul_f32_e32 v46, v49, v96
	v_pk_mul_f32 v[60:61], v[42:43], v[86:87] op_sel:[1,1] op_sel_hi:[1,0]
	v_pk_fma_f32 v[56:57], v[48:49], v[96:97], v[46:47] op_sel:[0,1,0] op_sel_hi:[1,0,0]
	v_pk_mul_f32 v[48:49], v[42:43], v[86:87]
	v_pk_fma_f32 v[42:43], v[42:43], v[86:87], v[60:61] op_sel_hi:[0,1,1]
	v_mul_f32_e32 v42, v45, v89
	v_pk_fma_f32 v[62:63], v[44:45], v[88:89], v[42:43] op_sel_hi:[1,1,0] neg_lo:[0,0,1] neg_hi:[0,0,1]
	v_mul_f32_e32 v42, v45, v88
	v_pk_fma_f32 v[64:65], v[44:45], v[88:89], v[42:43] op_sel:[0,1,0] op_sel_hi:[1,0,0]
	v_sub_f32_e32 v46, v50, v52
	v_sub_f32_e32 v42, v48, v60
	v_mov_b32_e32 v48, v54
	v_mov_b32_e32 v49, v56
	v_mov_b32_e32 v44, v62
	v_mov_b32_e32 v45, v64
; __device__ __forceinline__ unsigned cvt_pk_bf16(float lo, float hi) { unsigned r; asm("v_cvt_pk_bf16_f32 %0, %1, %2" : "=v"(r) : "v"(lo), "v"(hi)); return r; }
;     __device__ __forceinline__ void operator()(const AccT& acc, const Unit& u, int wr, int wc, int fr, int fq) const {
;     ...
; #pragma unroll
;         for (int ai = 0; ai < 2; ++ai)
; #pragma unroll
;             for (int m = 0; m < 4; ++m) {
;                 const int rl = ai * 128 + wr * 64 + m * 16 + fr;
;                 bf16_t* rowp = base + (size_t)(u.pm * 256 + rl) * ldo + hh * 256 + wc * 32 + 8 * fq;
; #pragma unroll
;                 for (int bj = 0; bj < 2; ++bj) {
;                     f32x4 v0 = acc[ai][bj][m][0], v1 = acc[ai][bj][m][1];
;                     if (lat) {
;                         const f32x4 c01 = bj ? ctC[m][0] : ctR[ai][0], c23 = bj ? ctC[m][1] : ctR[ai][1];
;                         f32x4 r0, r1;
;                         r0[0] = v0[0] * c01[0] - v0[1] * c01[1]; r0[1] = v0[0] * c01[1] + v0[1] * c01[0];
;                         r0[2] = v0[2] * c01[2] - v0[3] * c01[3]; r0[3] = v0[2] * c01[3] + v0[3] * c01[2];
;                         r1[0] = v1[0] * c23[0] - v1[1] * c23[1]; r1[1] = v1[0] * c23[1] + v1[1] * c23[0];
;                         r1[2] = v1[2] * c23[2] - v1[3] * c23[3]; r1[3] = v1[2] * c23[3] + v1[3] * c23[2];
;                         v0 = r0; v1 = r1;
;                     }
;                     v0 = v0 * osc; v1 = v1 * osc;
;                     u32x4 w; w.x = cvt_pk_bf16(v0[0], v0[1]); w.y = cvt_pk_bf16(v0[2], v0[3]); w.z = cvt_pk_bf16(v1[0], v1[1]); w.w = cvt_pk_bf16(v1[2], v1[3]);
;                     *(u32x4*)(rowp + bj * 128) = w;
.LBB0_356:
	s_nop 0
	v_add_u32_e32 v50, 0x90, v194
	v_ashrrev_i32_e32 v51, 31, v50
	v_lshlrev_b64 v[50:51], s10, v[50:51]
	v_lshl_add_u64 v[50:51], v[50:51], 1, v[196:197]
	v_pk_mul_f32 v[52:53], v[58:59], v[44:45]
	v_pk_mul_f32 v[44:45], v[192:193], v[42:43]
	s_and_b64 vcc, exec, s[4:5]
	v_pk_mul_f32 v[48:49], v[58:59], v[48:49]
	v_pk_mul_f32 v[46:47], v[192:193], v[46:47]
	v_cvt_pk_bf16_f32 v43, v48, v49
	v_cvt_pk_bf16_f32 v44, v44, v45
	v_cvt_pk_bf16_f32 v45, v52, v53
	s_nop 0
	v_cvt_pk_bf16_f32 v42, v46, v47
	global_store_dwordx4 v[50:51], v[42:45], off
	s_cbranch_vccnz .LBB0_358
	s_nop 1
	v_pk_mul_f32 v[44:45], v[38:39], v[134:135] op_sel:[1,1] op_sel_hi:[1,0]
	v_pk_mul_f32 v[42:43], v[38:39], v[134:135]
	v_pk_fma_f32 v[38:39], v[38:39], v[134:135], v[44:45] op_sel_hi:[0,1,1]
	v_mul_f32_e32 v38, v41, v137
	v_pk_fma_f32 v[46:47], v[40:41], v[136:137], v[38:39] op_sel_hi:[1,1,0] neg_lo:[0,0,1] neg_hi:[0,0,1]
	v_mul_f32_e32 v38, v41, v136
	v_pk_mul_f32 v[52:53], v[34:35], v[130:131] op_sel:[1,1] op_sel_hi:[1,0]
	v_pk_fma_f32 v[48:49], v[40:41], v[136:137], v[38:39] op_sel:[0,1,0] op_sel_hi:[1,0,0]
	v_pk_mul_f32 v[40:41], v[34:35], v[130:131]
	v_pk_fma_f32 v[34:35], v[34:35], v[130:131], v[52:53] op_sel_hi:[0,1,1]
	v_mul_f32_e32 v34, v37, v133
	v_pk_fma_f32 v[54:55], v[36:37], v[132:133], v[34:35] op_sel_hi:[1,1,0] neg_lo:[0,0,1] neg_hi:[0,0,1]
	v_mul_f32_e32 v34, v37, v132
	v_pk_fma_f32 v[56:57], v[36:37], v[132:133], v[34:35] op_sel:[0,1,0] op_sel_hi:[1,0,0]
	v_sub_f32_e32 v38, v42, v44
	v_sub_f32_e32 v34, v40, v52
	v_mov_b32_e32 v40, v46
	v_mov_b32_e32 v41, v48
	v_mov_b32_e32 v36, v54
	v_mov_b32_e32 v37, v56
.LBB0_358:
	s_nop 0
	v_mov_b32_e32 v42, v192
	v_mov_b32_e32 v43, v192
	v_pk_mul_f32 v[44:45], v[42:43], v[36:37]
	v_pk_mul_f32 v[36:37], v[192:193], v[34:35]
	s_and_b64 vcc, exec, s[4:5]
	v_pk_mul_f32 v[40:41], v[42:43], v[40:41]
	v_pk_mul_f32 v[38:39], v[192:193], v[38:39]
	v_cvt_pk_bf16_f32 v35, v40, v41
	v_cvt_pk_bf16_f32 v36, v36, v37
	v_cvt_pk_bf16_f32 v37, v44, v45
	s_nop 0
	v_cvt_pk_bf16_f32 v34, v38, v39
	global_store_dwordx4 v[50:51], v[34:37], off offset:256
	s_cbranch_vccnz .LBB0_360
	s_nop 1
	v_pk_mul_f32 v[36:37], v[30:31], v[94:95] op_sel:[1,1] op_sel_hi:[1,0]
	v_pk_mul_f32 v[34:35], v[30:31], v[94:95]
	v_pk_fma_f32 v[30:31], v[30:31], v[94:95], v[36:37] op_sel_hi:[0,1,1]
	v_mul_f32_e32 v30, v33, v97
	v_pk_fma_f32 v[38:39], v[32:33], v[96:97], v[30:31] op_sel_hi:[1,1,0] neg_lo:[0,0,1] neg_hi:[0,0,1]
	v_mul_f32_e32 v30, v33, v96
	v_pk_mul_f32 v[44:45], v[26:27], v[86:87] op_sel:[1,1] op_sel_hi:[1,0]
	v_pk_fma_f32 v[40:41], v[32:33], v[96:97], v[30:31] op_sel:[0,1,0] op_sel_hi:[1,0,0]
	v_pk_mul_f32 v[32:33], v[26:27], v[86:87]
	v_pk_fma_f32 v[26:27], v[26:27], v[86:87], v[44:45] op_sel_hi:[0,1,1]
	v_mul_f32_e32 v26, v29, v89
	v_pk_fma_f32 v[46:47], v[28:29], v[88:89], v[26:27] op_sel_hi:[1,1,0] neg_lo:[0,0,1] neg_hi:[0,0,1]
	v_mul_f32_e32 v26, v29, v88
	v_pk_fma_f32 v[48:49], v[28:29], v[88:89], v[26:27] op_sel:[0,1,0] op_sel_hi:[1,0,0]
	v_sub_f32_e32 v30, v34, v36
	v_sub_f32_e32 v26, v32, v44
	v_mov_b32_e32 v32, v38
	v_mov_b32_e32 v33, v40
	v_mov_b32_e32 v28, v46
	v_mov_b32_e32 v29, v48
; __device__ __forceinline__ unsigned cvt_pk_bf16(float lo, float hi) { unsigned r; asm("v_cvt_pk_bf16_f32 %0, %1, %2" : "=v"(r) : "v"(lo), "v"(hi)); return r; }
;     __device__ __forceinline__ void operator()(const AccT& acc, const Unit& u, int wr, int wc, int fr, int fq) const {
;     ...
; #pragma unroll
;         for (int ai = 0; ai < 2; ++ai)
; #pragma unroll
;             for (int m = 0; m < 4; ++m) {
;                 const int rl = ai * 128 + wr * 64 + m * 16 + fr;
;                 bf16_t* rowp = base + (size_t)(u.pm * 256 + rl) * ldo + hh * 256 + wc * 32 + 8 * fq;
; #pragma unroll
;                 for (int bj = 0; bj < 2; ++bj) {
;                     f32x4 v0 = acc[ai][bj][m][0], v1 = acc[ai][bj][m][1];
;                     if (lat) {
;                         const f32x4 c01 = bj ? ctC[m][0] : ctR[ai][0], c23 = bj ? ctC[m][1] : ctR[ai][1];
;                         f32x4 r0, r1;
;                         r0[0] = v0[0] * c01[0] - v0[1] * c01[1]; r0[1] = v0[0] * c01[1] + v0[1] * c01[0];
;                         r0[2] = v0[2] * c01[2] - v0[3] * c01[3]; r0[3] = v0[2] * c01[3] + v0[3] * c01[2];
;                         r1[0] = v1[0] * c23[0] - v1[1] * c23[1]; r1[1] = v1[0] * c23[1] + v1[1] * c23[0];
;                         r1[2] = v1[2] * c23[2] - v1[3] * c23[3]; r1[3] = v1[2] * c23[3] + v1[3] * c23[2];
;                         v0 = r0; v1 = r1;
;                     }
;                     v0 = v0 * osc; v1 = v1 * osc;
;                     u32x4 w; w.x = cvt_pk_bf16(v0[0], v0[1]); w.y = cvt_pk_bf16(v0[2], v0[3]); w.z = cvt_pk_bf16(v1[0], v1[1]); w.w = cvt_pk_bf16(v1[2], v1[3]);
;                     *(u32x4*)(rowp + bj * 128) = w;
.LBB0_360:
	s_nop 0
	v_add_u32_e32 v34, 0xa0, v194
	v_ashrrev_i32_e32 v35, 31, v34
	v_lshlrev_b64 v[34:35], s10, v[34:35]
	v_lshl_add_u64 v[34:35], v[34:35], 1, v[196:197]
	v_pk_mul_f32 v[36:37], v[42:43], v[28:29]
	v_pk_mul_f32 v[28:29], v[192:193], v[26:27]
	s_and_b64 vcc, exec, s[4:5]
	v_pk_mul_f32 v[32:33], v[42:43], v[32:33]
	v_pk_mul_f32 v[30:31], v[192:193], v[30:31]
	v_cvt_pk_bf16_f32 v27, v32, v33
	v_cvt_pk_bf16_f32 v28, v28, v29
	v_cvt_pk_bf16_f32 v29, v36, v37
	s_nop 0
	v_cvt_pk_bf16_f32 v26, v30, v31
	global_store_dwordx4 v[34:35], v[26:29], off
	s_cbranch_vccnz .LBB0_362
	s_nop 1
	v_pk_mul_f32 v[28:29], v[22:23], v[110:111] op_sel:[1,1] op_sel_hi:[1,0]
	v_pk_mul_f32 v[26:27], v[22:23], v[110:111]
	v_pk_fma_f32 v[22:23], v[22:23], v[110:111], v[28:29] op_sel_hi:[0,1,1]
	v_mul_f32_e32 v22, v25, v113
	v_pk_fma_f32 v[30:31], v[24:25], v[112:113], v[22:23] op_sel_hi:[1,1,0] neg_lo:[0,0,1] neg_hi:[0,0,1]
	v_mul_f32_e32 v22, v25, v112
	v_pk_mul_f32 v[36:37], v[18:19], v[106:107] op_sel:[1,1] op_sel_hi:[1,0]
	v_pk_fma_f32 v[32:33], v[24:25], v[112:113], v[22:23] op_sel:[0,1,0] op_sel_hi:[1,0,0]
	v_pk_mul_f32 v[24:25], v[18:19], v[106:107]
	v_pk_fma_f32 v[18:19], v[18:19], v[106:107], v[36:37] op_sel_hi:[0,1,1]
	v_mul_f32_e32 v18, v21, v109
	v_pk_fma_f32 v[38:39], v[20:21], v[108:109], v[18:19] op_sel_hi:[1,1,0] neg_lo:[0,0,1] neg_hi:[0,0,1]
	v_mul_f32_e32 v18, v21, v108
	v_pk_fma_f32 v[40:41], v[20:21], v[108:109], v[18:19] op_sel:[0,1,0] op_sel_hi:[1,0,0]
	v_sub_f32_e32 v22, v26, v28
	v_sub_f32_e32 v18, v24, v36
	v_mov_b32_e32 v24, v30
	v_mov_b32_e32 v25, v32
	v_mov_b32_e32 v20, v38
	v_mov_b32_e32 v21, v40
.LBB0_362:
	s_nop 0
	v_mov_b32_e32 v26, v192
	v_mov_b32_e32 v27, v192
	v_pk_mul_f32 v[28:29], v[26:27], v[20:21]
	v_pk_mul_f32 v[20:21], v[192:193], v[18:19]
	s_and_b64 vcc, exec, s[4:5]
	v_pk_mul_f32 v[24:25], v[26:27], v[24:25]
	v_pk_mul_f32 v[22:23], v[192:193], v[22:23]
	v_cvt_pk_bf16_f32 v19, v24, v25
	v_cvt_pk_bf16_f32 v20, v20, v21
	v_cvt_pk_bf16_f32 v21, v28, v29
	s_nop 0
	v_cvt_pk_bf16_f32 v18, v22, v23
	global_store_dwordx4 v[34:35], v[18:21], off offset:256
	s_cbranch_vccnz .LBB0_364
	s_nop 1
	v_pk_mul_f32 v[20:21], v[14:15], v[94:95] op_sel:[1,1] op_sel_hi:[1,0]
	v_pk_mul_f32 v[18:19], v[14:15], v[94:95]
	v_pk_fma_f32 v[14:15], v[14:15], v[94:95], v[20:21] op_sel_hi:[0,1,1]
	v_mul_f32_e32 v14, v17, v97
	v_pk_fma_f32 v[22:23], v[16:17], v[96:97], v[14:15] op_sel_hi:[1,1,0] neg_lo:[0,0,1] neg_hi:[0,0,1]
	v_mul_f32_e32 v14, v17, v96
	v_pk_mul_f32 v[28:29], v[10:11], v[86:87] op_sel:[1,1] op_sel_hi:[1,0]
	v_pk_fma_f32 v[24:25], v[16:17], v[96:97], v[14:15] op_sel:[0,1,0] op_sel_hi:[1,0,0]
	v_pk_mul_f32 v[16:17], v[10:11], v[86:87]
	v_pk_fma_f32 v[10:11], v[10:11], v[86:87], v[28:29] op_sel_hi:[0,1,1]
	v_mul_f32_e32 v10, v13, v89
	v_pk_fma_f32 v[30:31], v[12:13], v[88:89], v[10:11] op_sel_hi:[1,1,0] neg_lo:[0,0,1] neg_hi:[0,0,1]
	v_mul_f32_e32 v10, v13, v88
	v_pk_fma_f32 v[32:33], v[12:13], v[88:89], v[10:11] op_sel:[0,1,0] op_sel_hi:[1,0,0]
	v_sub_f32_e32 v14, v18, v20
	v_sub_f32_e32 v10, v16, v28
	v_mov_b32_e32 v16, v22
	v_mov_b32_e32 v17, v24
	v_mov_b32_e32 v12, v30
	v_mov_b32_e32 v13, v32
.LBB0_364:
	s_nop 0
	v_add_u32_e32 v18, 0xb0, v194
	v_ashrrev_i32_e32 v19, 31, v18
	v_lshlrev_b64 v[18:19], s10, v[18:19]
	v_lshl_add_u64 v[18:19], v[18:19], 1, v[196:197]
	v_pk_mul_f32 v[20:21], v[26:27], v[12:13]
	v_pk_mul_f32 v[12:13], v[192:193], v[10:11]
	s_and_b64 vcc, exec, s[4:5]
	v_pk_mul_f32 v[16:17], v[26:27], v[16:17]
	v_pk_mul_f32 v[14:15], v[192:193], v[14:15]
	v_cvt_pk_bf16_f32 v11, v16, v17
	v_cvt_pk_bf16_f32 v12, v12, v13
	v_cvt_pk_bf16_f32 v13, v20, v21
	s_nop 0
	v_cvt_pk_bf16_f32 v10, v14, v15
	global_store_dwordx4 v[18:19], v[10:13], off
	s_cbranch_vccnz .LBB0_325
	s_nop 1
	v_pk_mul_f32 v[12:13], v[6:7], v[82:83] op_sel:[1,1] op_sel_hi:[1,0]
	v_pk_mul_f32 v[10:11], v[6:7], v[82:83]
	v_pk_fma_f32 v[6:7], v[6:7], v[82:83], v[12:13] op_sel_hi:[0,1,1]
	v_mul_f32_e32 v6, v9, v85
	v_pk_fma_f32 v[14:15], v[8:9], v[84:85], v[6:7] op_sel_hi:[1,1,0] neg_lo:[0,0,1] neg_hi:[0,0,1]
	v_mul_f32_e32 v6, v9, v84
	v_pk_mul_f32 v[20:21], v[2:3], v[74:75] op_sel:[1,1] op_sel_hi:[1,0]
	v_pk_fma_f32 v[16:17], v[8:9], v[84:85], v[6:7] op_sel:[0,1,0] op_sel_hi:[1,0,0]
	v_pk_mul_f32 v[8:9], v[2:3], v[74:75]
	v_pk_fma_f32 v[2:3], v[2:3], v[74:75], v[20:21] op_sel_hi:[0,1,1]
	v_mul_f32_e32 v2, v5, v77
	v_pk_fma_f32 v[22:23], v[4:5], v[76:77], v[2:3] op_sel_hi:[1,1,0] neg_lo:[0,0,1] neg_hi:[0,0,1]
	v_mul_f32_e32 v2, v5, v76
	v_pk_fma_f32 v[24:25], v[4:5], v[76:77], v[2:3] op_sel:[0,1,0] op_sel_hi:[1,0,0]
	v_sub_f32_e32 v6, v10, v12
	v_sub_f32_e32 v2, v8, v20
	v_mov_b32_e32 v8, v14
	v_mov_b32_e32 v9, v16
	v_mov_b32_e32 v4, v22
	v_mov_b32_e32 v5, v24
	s_branch .LBB0_325
